# fused epilogue statistic exchange: the four tagged slot loads of a poll issued together instead of one round trip each
# speedup vs baseline: 1.0126x; 1.0010x over previous
.LBB0_373:
	s_mov_b64 s[0:1], 0
	v_mov_b32_e32 v184, 0x3a83126f
	s_and_saveexec_b64 s[4:5], s[36:37]
	s_cbranch_execz .LBB0_375
	global_load_dwordx2 v[232:233], v[180:181], off sc1
	global_load_dwordx2 v[234:235], v[180:181], off offset:8 sc1
	global_load_dwordx2 v[236:237], v[180:181], off offset:16 sc1
	global_load_dwordx2 v[184:185], v[180:181], off offset:24 sc1
	s_waitcnt vmcnt(0)
	v_cmp_ne_u32_e32 vcc, s28, v233
	v_add_f32_e32 v186, 0, v232
	v_cmp_ne_u32_e64 s[0:1], s28, v235
	v_add_f32_e32 v186, v186, v234
	s_nop 1
	s_or_b64 s[0:1], vcc, s[0:1]
	v_cmp_ne_u32_e32 vcc, s28, v237
	v_add_f32_e32 v186, v186, v236
	s_nop 1
	s_or_b64 s[0:1], s[0:1], vcc
	v_add_f32_e32 v184, v186, v184
	v_cmp_ne_u32_e32 vcc, s28, v185
	v_fmamk_f32 v184, v184, 0x3a800000, v213
	s_or_b64 s[12:13], s[0:1], vcc
	v_cmp_gt_f32_e32 vcc, s78, v184
	v_mul_f32_e32 v185, 0x4f800000, v184
	s_nop 0
	v_cndmask_b32_e32 v184, v184, v185, vcc
	v_sqrt_f32_e32 v185, v184
	s_nop 0
	v_add_u32_e32 v186, -1, v185
	v_fma_f32 v187, -v186, v185, v184
	v_cmp_ge_f32_e64 s[0:1], 0, v187
	v_add_u32_e32 v187, 1, v185
	s_nop 0
	v_cndmask_b32_e64 v186, v185, v186, s[0:1]
	v_fma_f32 v185, -v187, v185, v184
	v_cmp_lt_f32_e64 s[0:1], 0, v185
	s_nop 1
	v_cndmask_b32_e64 v185, v186, v187, s[0:1]
	v_mul_f32_e32 v186, 0x37800000, v185
	v_cndmask_b32_e32 v185, v185, v186, vcc
	v_cmp_class_f32_e32 vcc, v184, v219
	s_and_b64 s[0:1], s[12:13], exec
	s_nop 0
	v_cndmask_b32_e32 v184, v185, v184, vcc

.LBB0_447:
	s_mov_b64 s[0:1], 0
	v_mov_b32_e32 v84, 0x3a83126f
	s_and_saveexec_b64 s[4:5], s[36:37]
	s_cbranch_execz .LBB0_449
	global_load_dwordx2 v[232:233], v[0:1], off sc1
	global_load_dwordx2 v[234:235], v[0:1], off offset:8 sc1
	global_load_dwordx2 v[236:237], v[0:1], off offset:16 sc1
	global_load_dwordx2 v[84:85], v[0:1], off offset:24 sc1
	s_waitcnt vmcnt(0)
	v_cmp_ne_u32_e32 vcc, s28, v233
	v_add_f32_e32 v86, 0, v232
	v_cmp_ne_u32_e64 s[0:1], s28, v235
	v_add_f32_e32 v86, v86, v234
	s_nop 1
	s_or_b64 s[0:1], vcc, s[0:1]
	v_cmp_ne_u32_e32 vcc, s28, v237
	v_add_f32_e32 v86, v86, v236
	s_nop 1
	s_or_b64 s[0:1], s[0:1], vcc
	v_add_f32_e32 v84, v86, v84
	v_cmp_ne_u32_e32 vcc, s28, v85
	v_fmamk_f32 v84, v84, 0x3a800000, v213
	s_or_b64 s[8:9], s[0:1], vcc
	v_cmp_gt_f32_e32 vcc, s78, v84
	v_mul_f32_e32 v85, 0x4f800000, v84
	s_nop 0
	v_cndmask_b32_e32 v84, v84, v85, vcc
	v_sqrt_f32_e32 v85, v84
	s_nop 0
	v_add_u32_e32 v86, -1, v85
	v_fma_f32 v87, -v86, v85, v84
	v_cmp_ge_f32_e64 s[0:1], 0, v87
	v_add_u32_e32 v87, 1, v85
	s_nop 0
	v_cndmask_b32_e64 v86, v85, v86, s[0:1]
	v_fma_f32 v85, -v87, v85, v84
	v_cmp_lt_f32_e64 s[0:1], 0, v85
	s_nop 1
	v_cndmask_b32_e64 v85, v86, v87, s[0:1]
	v_mul_f32_e32 v86, 0x37800000, v85
	v_cndmask_b32_e32 v85, v85, v86, vcc
	v_cmp_class_f32_e32 vcc, v84, v219
	s_and_b64 s[0:1], s[8:9], exec
	s_nop 0
	v_cndmask_b32_e32 v84, v85, v84, vcc

.LBB0_628:
	s_mov_b64 s[0:1], 0
	v_mov_b32_e32 v222, 0x3a83126f
	s_and_saveexec_b64 s[6:7], s[36:37]
	s_cbranch_execz .LBB0_630
	global_load_dwordx2 v[232:233], v[216:217], off sc1
	global_load_dwordx2 v[234:235], v[216:217], off offset:8 sc1
	global_load_dwordx2 v[236:237], v[216:217], off offset:16 sc1
	global_load_dwordx2 v[224:225], v[216:217], off offset:24 sc1
	s_waitcnt vmcnt(0)
	v_cmp_ne_u32_e32 vcc, s28, v233
	v_add_f32_e32 v222, 0, v232
	v_cmp_ne_u32_e64 s[0:1], s28, v235
	v_add_f32_e32 v222, v222, v234
	s_nop 1
	s_or_b64 s[0:1], vcc, s[0:1]
	v_cmp_ne_u32_e32 vcc, s28, v237
	v_add_f32_e32 v222, v222, v236
	s_nop 1
	s_or_b64 s[0:1], s[0:1], vcc
	v_add_f32_e32 v222, v222, v224
	v_cmp_ne_u32_e32 vcc, s28, v225
	v_fmamk_f32 v222, v222, 0x3a800000, v213
	s_or_b64 s[12:13], s[0:1], vcc
	v_cmp_gt_f32_e32 vcc, s78, v222
	v_mul_f32_e32 v224, 0x4f800000, v222
	s_nop 0
	v_cndmask_b32_e32 v222, v222, v224, vcc
	v_sqrt_f32_e32 v224, v222
	s_nop 0
	v_add_u32_e32 v225, -1, v224
	v_fma_f32 v227, -v225, v224, v222
	v_cmp_ge_f32_e64 s[0:1], 0, v227
	v_add_u32_e32 v227, 1, v224
	s_nop 0
	v_cndmask_b32_e64 v225, v224, v225, s[0:1]
	v_fma_f32 v224, -v227, v224, v222
	v_cmp_lt_f32_e64 s[0:1], 0, v224
	s_nop 1
	v_cndmask_b32_e64 v224, v225, v227, s[0:1]
	v_mul_f32_e32 v225, 0x37800000, v224
	v_cndmask_b32_e32 v224, v224, v225, vcc
	v_cmp_class_f32_e32 vcc, v222, v219
	s_and_b64 s[0:1], s[12:13], exec
	s_nop 0
	v_cndmask_b32_e32 v222, v224, v222, vcc

.LBB0_657:
	s_mov_b64 s[0:1], 0
	v_mov_b32_e32 v130, 0x3a83126f
	s_and_saveexec_b64 s[6:7], s[36:37]
	s_cbranch_execz .LBB0_659
	global_load_dwordx2 v[232:233], v[128:129], off sc1
	global_load_dwordx2 v[234:235], v[128:129], off offset:8 sc1
	global_load_dwordx2 v[236:237], v[128:129], off offset:16 sc1
	global_load_dwordx2 v[130:131], v[128:129], off offset:24 sc1
	s_waitcnt vmcnt(0)
	v_cmp_ne_u32_e32 vcc, s28, v233
	v_add_f32_e32 v132, 0, v232
	v_cmp_ne_u32_e64 s[0:1], s28, v235
	v_add_f32_e32 v132, v132, v234
	s_nop 1
	s_or_b64 s[0:1], vcc, s[0:1]
	v_cmp_ne_u32_e32 vcc, s28, v237
	v_add_f32_e32 v132, v132, v236
	s_nop 1
	s_or_b64 s[0:1], s[0:1], vcc
	v_add_f32_e32 v130, v132, v130
	v_cmp_ne_u32_e32 vcc, s28, v131
	v_fmamk_f32 v130, v130, 0x3a800000, v213
	s_or_b64 s[10:11], s[0:1], vcc
	v_cmp_gt_f32_e32 vcc, s78, v130
	v_mul_f32_e32 v131, 0x4f800000, v130
	s_nop 0
	v_cndmask_b32_e32 v130, v130, v131, vcc
	v_sqrt_f32_e32 v131, v130
	s_nop 0
	v_add_u32_e32 v132, -1, v131
	v_fma_f32 v133, -v132, v131, v130
	v_cmp_ge_f32_e64 s[0:1], 0, v133
	v_add_u32_e32 v133, 1, v131
	s_nop 0
	v_cndmask_b32_e64 v132, v131, v132, s[0:1]
	v_fma_f32 v131, -v133, v131, v130
	v_cmp_lt_f32_e64 s[0:1], 0, v131
	s_nop 1
	v_cndmask_b32_e64 v131, v132, v133, s[0:1]
	v_mul_f32_e32 v132, 0x37800000, v131
	v_cndmask_b32_e32 v131, v131, v132, vcc
	v_cmp_class_f32_e32 vcc, v130, v219
	s_and_b64 s[0:1], s[10:11], exec
	s_nop 0
	v_cndmask_b32_e32 v130, v131, v130, vcc
